# unit order remap also in S5 (4x8 panels per XCD round) and S3 (2x16): the activation operand of each phase is streamed once per XCD
# speedup vs baseline: 1.0445x; 1.0039x over previous
.LBB0_582:
	s_cmpk_lt_i32 s80, 0x400
	v_readlane_b32 s0, v255, 0
	s_cselect_b64 s[4:5], -1, 0
	s_lshr_b32 s0, s0, 29
	s_add_i32 s0, s80, s0
	s_ashr_i32 s1, s0, 3
	s_and_b32 s0, s0, -8
	s_sub_i32 s0, s80, s0
	s_cmp_lt_i32 s0, 0
	v_writelane_b32 v255, s1, 11
	s_cselect_b64 s[8:9], -1, 0
	s_cmp_gt_i32 s0, -1
	v_writelane_b32 v255, s0, 10
	s_cselect_b64 s[0:1], -1, 0
	v_writelane_b32 v255, s0, 12
	s_cmpk_gt_i32 s80, 0x3ff
	v_mbcnt_lo_u32_b32 v8, -1, 0
	v_mbcnt_hi_u32_b32 v8, -1, v8
	s_nop 0
	v_writelane_b32 v255, s1, 13
	s_cbranch_scc1 .LBB0_584
	v_readlane_b32 s0, v255, 10
	s_lshl_b32 s3, s0, 7
	s_mul_i32 s6, s0, 0x81
	s_and_b64 s[0:1], s[8:9], exec
	s_cselect_b32 s0, s6, s3
	v_readlane_b32 s1, v255, 11
	s_add_i32 s0, s0, s1
	s_ashr_i32 s1, s0, 31
	s_lshr_b32 s1, s1, 25
	s_add_i32 s1, s0, s1
	s_ashr_i32 s3, s1, 7
	s_and_b32 s1, s1, 0xffffff80
	s_sub_i32 s0, s0, s1
	s_bfe_i32 s1, s0, 0x80000
	s_bfe_u32 s1, s1, 0x3000c
	s_add_i32 s1, s0, s1
	s_bfe_i32 s6, s1, 0x80000
	s_and_b32 s1, s1, 0xf8
	s_sub_i32 s0, s0, s1
	s_lshl_b32 s3, s3, 3
	s_sext_i32_i16 s6, s6
	s_sext_i32_i8 s0, s0
	s_add_i32 s10, s3, s0
	s_ashr_i32 s16, s6, 3
	s_and_b32 s98, s10, 7
	s_lshl_b32 s99, s16, 3
	s_add_i32 s98, s98, s99
	s_lshr_b32 s100, s98, 5
	s_lshl_b32 s100, s100, 1
	s_and_b32 s98, s98, 0x1f
	s_lshr_b32 s16, s98, 1
	s_and_b32 s98, s98, 1
	s_and_b32 s10, s10, -8
	s_add_i32 s10, s10, s100
	s_add_i32 s10, s10, s98

.LBB0_595:
	s_ashr_i32 s11, s11, 3
	s_add_i32 s11, s20, s11
	s_ashr_i32 s17, s11, 31
	s_lshr_b32 s17, s17, 25
	s_add_i32 s17, s11, s17
	s_ashr_i32 s20, s17, 7
	s_lshl_b32 s20, s20, 3
	s_sub_i32 s26, 64, s20
	s_min_i32 s27, s26, 8
	s_abs_i32 s26, s27
	v_cvt_f32_u32_e32 v0, s26
	s_sub_i32 s29, 0, s26
	s_and_b32 s17, s17, 0xffffff80
	s_sub_i32 s11, s11, s17
	v_rcp_iflag_f32_e32 v0, v0
	s_abs_i32 s17, s11
	s_xor_b32 s28, s11, s27
	s_ashr_i32 s28, s28, 31
	v_mul_f32_e32 v0, 0x4f7ffffe, v0
	v_cvt_u32_f32_e32 v0, v0
	s_nop 0
	v_readfirstlane_b32 s30, v0
	s_mul_i32 s29, s29, s30
	s_mul_hi_u32 s29, s30, s29
	s_add_i32 s30, s30, s29
	s_mul_hi_u32 s29, s17, s30
	s_mul_i32 s30, s29, s26
	s_sub_i32 s17, s17, s30
	s_add_i32 s31, s29, 1
	s_sub_i32 s30, s17, s26
	s_cmp_ge_u32 s17, s26
	s_cselect_b32 s29, s31, s29
	s_cselect_b32 s17, s30, s17
	s_add_i32 s30, s29, 1
	s_cmp_ge_u32 s17, s26
	s_cselect_b32 s17, s30, s29
	s_xor_b32 s17, s17, s28
	s_sub_i32 s26, s17, s28
	s_mul_i32 s17, s26, s27
	s_sub_i32 s11, s11, s17
	s_add_i32 s28, s20, s11
	s_and_b32 s98, s28, 7
	s_lshl_b32 s99, s26, 3
	s_add_i32 s98, s98, s99
	s_lshr_b32 s100, s98, 5
	s_lshl_b32 s100, s100, 1
	s_and_b32 s98, s98, 0x1f
	s_lshr_b32 s26, s98, 1
	s_and_b32 s98, s98, 1
	s_and_b32 s28, s28, -8
	s_add_i32 s28, s28, s100
	s_add_i32 s28, s28, s98

.LBB0_1318:
	v_readlane_b32 s1, v255, 11
	s_add_i32 s0, s0, s1
	s_ashr_i32 s1, s0, 31
	s_lshr_b32 s1, s1, 26
	s_add_i32 s1, s0, s1
	s_ashr_i32 s2, s1, 6
	s_andn2_b32 s1, s1, 63
	s_sub_i32 s0, s0, s1
	s_bfe_i32 s1, s0, 0x80000
	s_bfe_u32 s1, s1, 0x3000c
	s_add_i32 s1, s0, s1
	s_bfe_i32 s3, s1, 0x80000
	s_and_b32 s1, s1, 0xf8
	s_sub_i32 s0, s0, s1
	s_lshl_b32 s2, s2, 3
	s_sext_i32_i16 s3, s3
	s_sext_i32_i8 s0, s0
	s_add_i32 s28, s2, s0
	s_ashr_i32 s30, s3, 3
	s_lshr_b32 s98, s30, 2
	s_bfe_u32 s99, s28, 0x10002
	s_and_b32 s100, s30, 3
	s_lshl_b32 s100, s100, 1
	s_or_b32 s30, s100, s99
	s_and_b32 s99, s28, -8
	s_and_b32 s100, s28, 3
	s_lshl_b32 s98, s98, 2
	s_or_b32 s28, s99, s100
	s_or_b32 s28, s28, s98

.LBB0_1330:
	s_ashr_i32 s20, s22, 3
	s_add_i32 s20, s24, s20
	s_ashr_i32 s21, s20, 31
	s_lshr_b32 s21, s21, 26
	s_add_i32 s21, s20, s21
	s_ashr_i32 s22, s21, 6
	s_lshl_b32 s22, s22, 3
	s_sub_i32 s23, 64, s22
	s_min_i32 s23, s23, 8
	s_abs_i32 s24, s23
	v_cvt_f32_u32_e32 v0, s24
	s_sub_i32 s26, 0, s24
	s_andn2_b32 s21, s21, 63
	s_sub_i32 s21, s20, s21
	v_rcp_iflag_f32_e32 v0, v0
	s_abs_i32 s20, s21
	s_xor_b32 s25, s21, s23
	s_ashr_i32 s25, s25, 31
	v_mul_f32_e32 v0, 0x4f7ffffe, v0
	v_cvt_u32_f32_e32 v0, v0
	s_nop 0
	v_readfirstlane_b32 s27, v0
	s_mul_i32 s26, s26, s27
	s_mul_hi_u32 s26, s27, s26
	s_add_i32 s27, s27, s26
	s_mul_hi_u32 s26, s20, s27
	s_mul_i32 s27, s26, s24
	s_sub_i32 s20, s20, s27
	s_add_i32 s36, s26, 1
	s_sub_i32 s27, s20, s24
	s_cmp_ge_u32 s20, s24
	s_cselect_b32 s26, s36, s26
	s_cselect_b32 s20, s27, s20
	s_add_i32 s27, s26, 1
	s_cmp_ge_u32 s20, s24
	s_cselect_b32 s20, s27, s26
	s_xor_b32 s20, s20, s25
	s_sub_i32 s20, s20, s25
	s_mul_i32 s23, s20, s23
	s_sub_i32 s21, s21, s23
	s_add_i32 s22, s22, s21
	s_lshr_b32 s98, s20, 2
	s_bfe_u32 s99, s22, 0x10002
	s_and_b32 s100, s20, 3
	s_lshl_b32 s100, s100, 1
	s_or_b32 s20, s100, s99
	s_and_b32 s99, s22, -8
	s_and_b32 s100, s22, 3
	s_lshl_b32 s98, s98, 2
	s_or_b32 s22, s99, s100
	s_or_b32 s22, s22, s98
